# P0 end-of-phase grid sync routed through the XCD-hierarchical barrier instead of the cooperative-groups barrier
# baseline (speedup 1.0000x reference)
.LBB0_53:
	s_or_b64 exec, exec, s[0:1]
	s_ashr_i32 s27, s2, 31
	s_lshr_b32 s0, s27, 29
	s_add_i32 s0, s2, s0
	s_ashr_i32 s20, s0, 3
	s_and_b32 s0, s0, -8
	s_sub_i32 s21, s2, s0
	s_ashr_i32 s80, s86, 31
	s_add_u32 s96, s84, 0x4200
	s_addc_u32 s97, s85, 0
	s_add_u32 s98, s84, 0x4400
	s_addc_u32 s99, s85, 0
	s_add_u32 s64, s84, 0x4500
	s_addc_u32 s65, s85, 0
	s_add_u32 s66, s84, 0x4600
	s_addc_u32 s67, s85, 0
	s_add_u32 s68, s84, 0x4700
	s_addc_u32 s69, s85, 0
	s_add_u32 s24, s84, 0x4800
	s_addc_u32 s25, s85, 0
	s_add_u32 s0, s84, 0x4900
	s_addc_u32 s1, s85, 0
	v_writelane_b32 v250, s0, 17
	v_mov_b32_e32 v3, 0
	v_mov_b32_e32 v211, 1
	v_writelane_b32 v250, s1, 18
	s_add_u32 s0, s84, 0x4a00
	s_addc_u32 s1, s85, 0
	v_writelane_b32 v250, s0, 19
	v_mov_b32_e32 v192, 0x40400000
	v_mov_b32_e32 v213, 0x358637bd
	v_writelane_b32 v250, s1, 20
	s_add_u32 s0, s84, 0x4b00
	s_addc_u32 s1, s85, 0
	v_writelane_b32 v250, s0, 21
	v_mov_b32_e32 v219, 0x260
	v_mov_b32_e32 v221, 0x42800000
	v_writelane_b32 v250, s1, 22
	s_add_u32 s0, s84, 0x4c00
	s_addc_u32 s1, s85, 0
	v_writelane_b32 v250, s0, 23
	v_mov_b32_e32 v223, 0xff800000
	v_mbcnt_hi_u32_b32 v226, -1, v14
	v_writelane_b32 v250, s1, 24
	s_add_u32 s0, s84, 0x4d00
	s_addc_u32 s1, s85, 0
	v_writelane_b32 v250, s0, 25
	v_mov_b64_e32 v[194:195], 0x200
	v_mov_b64_e32 v[196:197], 0x1ff
	v_writelane_b32 v250, s1, 26
	s_add_u32 s0, s84, 0x4e00
	s_addc_u32 s1, s85, 0
	v_writelane_b32 v250, s0, 27
	v_mov_b64_e32 v[198:199], 0xb00
	v_mov_b64_e32 v[200:201], 0xaff
	v_writelane_b32 v250, s1, 28
	s_add_u32 s0, s84, 0x4f00
	s_addc_u32 s1, s85, 0
	v_writelane_b32 v250, s0, 29
	s_mov_b32 s82, 0xff800000
	s_mov_b32 s33, 0xffff0000
	v_writelane_b32 v250, s1, 30
	s_add_u32 s0, s84, 0x5000
	s_addc_u32 s1, s85, 0
	v_writelane_b32 v250, s0, 31
	s_movk_i32 s83, 0x1600
	s_mov_b32 s78, 0xf800000
	v_writelane_b32 v250, s1, 32
	s_add_u32 s0, s84, 0x5100
	s_addc_u32 s1, s85, 0
	v_writelane_b32 v250, s0, 33
	s_mov_b32 s46, 0
	s_mov_b64 s[22:23], 0x80
	v_writelane_b32 v250, s1, 34
	s_add_u32 s0, s84, 0x5200
	s_addc_u32 s1, s85, 0
	v_writelane_b32 v250, s0, 35
	s_mov_b64 s[34:35], 0x3ff80
	s_mov_b32 s26, 0xbfb8aa3b
	v_writelane_b32 v250, s1, 36
	s_add_u32 s0, s84, 0x5300
	s_addc_u32 s1, s85, 0
	v_writelane_b32 v250, s0, 37
	s_cmp_eq_u32 s28, 15
	s_barrier
	v_writelane_b32 v250, s1, 38
	s_cselect_b64 s[0:1], -1, 0
	v_writelane_b32 v250, s0, 39
	s_cmp_eq_u32 s28, 14
	s_nop 0
	v_writelane_b32 v250, s1, 40
	s_cselect_b64 s[0:1], -1, 0
	v_writelane_b32 v250, s0, 41
	s_cmp_eq_u32 s28, 13
	s_nop 0
	v_writelane_b32 v250, s1, 42
	s_cselect_b64 s[0:1], -1, 0
	v_writelane_b32 v250, s0, 43
	s_cmp_eq_u32 s28, 12
	s_nop 0
	v_writelane_b32 v250, s1, 44
	s_cselect_b64 s[0:1], -1, 0
	v_writelane_b32 v250, s0, 45
	s_cmp_eq_u32 s28, 11
	s_nop 0
	v_writelane_b32 v250, s1, 46
	s_cselect_b64 s[0:1], -1, 0
	v_writelane_b32 v250, s0, 47
	s_cmp_eq_u32 s28, 10
	s_nop 0
	v_writelane_b32 v250, s1, 48
	s_cselect_b64 s[0:1], -1, 0
	v_writelane_b32 v250, s0, 49
	s_cmp_eq_u32 s28, 9
	s_nop 0
	v_writelane_b32 v250, s1, 50
	s_cselect_b64 s[0:1], -1, 0
	v_writelane_b32 v250, s0, 51
	s_cmp_eq_u32 s28, 8
	s_nop 0
	v_writelane_b32 v250, s1, 52
	s_cselect_b64 s[0:1], -1, 0
	v_writelane_b32 v250, s0, 53
	s_cmp_eq_u32 s28, 7
	s_nop 0
	v_writelane_b32 v250, s1, 54
	s_cselect_b64 s[0:1], -1, 0
	v_writelane_b32 v250, s0, 55
	s_cmp_eq_u32 s28, 6
	s_nop 0
	v_writelane_b32 v250, s1, 56
	s_cselect_b64 s[0:1], -1, 0
	v_writelane_b32 v250, s0, 57
	s_cmp_eq_u32 s28, 5
	s_nop 0
	v_writelane_b32 v250, s1, 58
	s_cselect_b64 s[0:1], -1, 0
	v_writelane_b32 v250, s0, 59
	s_cmp_eq_u32 s28, 4
	s_nop 0
	v_writelane_b32 v250, s1, 60
	s_cselect_b64 s[0:1], -1, 0
	v_writelane_b32 v250, s0, 61
	s_cmp_eq_u32 s28, 3
	s_nop 0
	v_writelane_b32 v250, s1, 62
	s_cselect_b64 s[0:1], -1, 0
	v_writelane_b32 v250, s0, 63
	s_cmp_eq_u32 s28, 2
	s_nop 0
	v_writelane_b32 v249, s1, 0
	s_cselect_b64 s[0:1], -1, 0
	v_writelane_b32 v249, s0, 1
	s_cmp_eq_u32 s28, 1
	s_nop 0
	v_writelane_b32 v249, s1, 2
	s_cselect_b64 s[0:1], -1, 0
	v_writelane_b32 v249, s0, 3
	s_cmp_eq_u32 s28, 0
	s_nop 0
	v_writelane_b32 v249, s1, 4
	s_cselect_b64 s[0:1], -1, 0
	v_writelane_b32 v249, s0, 5
	s_nop 1
	v_writelane_b32 v249, s1, 6
	s_lshl_b32 s0, s28, 8
	s_add_u32 s0, s8, s0
	s_addc_u32 s1, s9, 0
	s_add_u32 s4, s0, 0x1400
	s_addc_u32 s5, s1, 0
	v_writelane_b32 v249, s4, 7
	s_add_u32 s0, s0, 0x2400
	s_addc_u32 s1, s1, 0
	v_writelane_b32 v249, s5, 8
	v_writelane_b32 v249, s0, 9
	v_readlane_b32 s4, v250, 1
	v_readlane_b32 s6, v250, 3
	v_writelane_b32 v249, s1, 10
	s_mul_i32 s0, s87, s86
	s_mul_i32 s81, s0, s3
	s_add_u32 s0, s84, 0x7400
	s_addc_u32 s1, s85, 0
	v_writelane_b32 v249, s0, 11
	v_readlane_b32 s7, v250, 4
	v_readlane_b32 s14, v250, 11
	v_writelane_b32 v249, s1, 12
	s_add_u32 s0, s84, 0x7500
	s_addc_u32 s1, s85, 0
	v_writelane_b32 v249, s0, 13
	s_cmpk_lt_i32 s2, 0x100
	v_readlane_b32 s15, v250, 12
	v_writelane_b32 v249, s1, 14
	s_cselect_b64 s[0:1], -1, 0
	v_writelane_b32 v249, s0, 15
	s_cmp_lg_u64 s[6:7], 0
	s_movk_i32 s87, 0x161
	v_writelane_b32 v249, s1, 16
	s_cselect_b64 s[0:1], -1, 0
	v_writelane_b32 v249, s0, 17
	s_cmp_lg_u64 s[14:15], 0
	v_readlane_b32 s5, v250, 2
	v_writelane_b32 v249, s1, 18
	s_cselect_b64 s[0:1], -1, 0
	v_writelane_b32 v249, s0, 19
	s_cmpk_lt_i32 s2, 0xb00
	v_readlane_b32 s19, v250, 16
	v_writelane_b32 v249, s1, 20
	s_cselect_b64 s[0:1], -1, 0
	v_writelane_b32 v249, s0, 21
	s_cmp_lt_i32 s21, 0
	s_mov_b32 s19, 0
	v_writelane_b32 v249, s1, 22
	s_cselect_b32 s0, s87, 0x160
	s_mul_i32 s0, s21, s0
	s_add_i32 s0, s0, s20
	s_mul_hi_i32 s1, s0, 0x2e8ba2e9
	s_lshr_b32 s3, s1, 31
	s_ashr_i32 s1, s1, 5
	s_add_i32 s1, s1, s3
	s_mul_i32 s3, s1, 0xb0
	s_sub_i32 s0, s0, s3
	s_bfe_u32 s3, s0, 0x3001c
	s_add_i32 s3, s0, s3
	s_and_b32 s4, s3, 0xfff8
	s_sub_i32 s0, s0, s4
	s_lshl_b32 s1, s1, 3
	s_sext_i32_i16 s3, s3
	s_sext_i32_i16 s0, s0
	v_writelane_b32 v249, s20, 23
	s_add_i32 s4, s1, s0
	s_ashr_i32 s0, s3, 3
	v_writelane_b32 v249, s0, 24
	s_lshr_b32 s0, s3, 3
	s_bfe_i64 s[0:1], s[0:1], 0x100000
	s_lshl_b64 s[0:1], s[0:1], 19
	v_writelane_b32 v249, s0, 25
	s_ashr_i32 s5, s4, 31
	s_movk_i32 s3, 0x7fff
	v_writelane_b32 v249, s1, 26
	v_writelane_b32 v249, s21, 27
	s_lshr_b32 s0, s21, 31
	v_writelane_b32 v249, s0, 28
	s_lshl_b32 s0, s2, 7
	v_writelane_b32 v249, s0, 29
	s_lshl_b32 s0, s86, 7
	v_writelane_b32 v249, s0, 30
	s_mov_b32 s0, s4
	v_writelane_b32 v249, s0, 31
	v_readlane_b32 s8, v250, 5
	v_readlane_b32 s9, v250, 6
	v_writelane_b32 v249, s1, 32
	s_lshl_b64 s[0:1], s[4:5], 19
	v_writelane_b32 v249, s0, 33
	v_readlane_b32 s10, v250, 7
	v_readlane_b32 s11, v250, 8
	v_writelane_b32 v249, s1, 34
	s_add_u32 s0, s84, 0x136b0080
	v_writelane_b32 v249, s0, 35
	s_addc_u32 s0, s85, 0
	v_writelane_b32 v249, s0, 36
	s_add_i32 s0, 0, 0x20020
	v_writelane_b32 v249, s0, 37
	s_add_i32 s0, 0, 0x20024
	v_writelane_b32 v249, s0, 38
	s_add_i32 s0, 0, 0x13000
	v_writelane_b32 v249, s0, 39
	v_writelane_b32 v249, s64, 40
	v_readlane_b32 s12, v250, 9
	v_readlane_b32 s13, v250, 10
	v_writelane_b32 v249, s65, 41
	v_writelane_b32 v249, s66, 42
	v_readlane_b32 s16, v250, 13
	v_readlane_b32 s17, v250, 14
	v_writelane_b32 v249, s67, 43
	v_writelane_b32 v249, s68, 44
	v_readlane_b32 s18, v250, 15
	s_nop 0
	v_writelane_b32 v249, s69, 45
	v_writelane_b32 v249, s24, 46
	s_nop 1
	v_writelane_b32 v249, s25, 47
	v_writelane_b32 v249, s88, 48
	s_nop 1
	v_writelane_b32 v249, s89, 49
	v_writelane_b32 v249, s90, 50
	v_writelane_b32 v249, s91, 51
	v_writelane_b32 v249, s92, 52
	v_writelane_b32 v249, s93, 53
	v_writelane_b32 v249, s94, 54
	v_writelane_b32 v249, s95, 55
	v_writelane_b32 v249, s76, 56
	s_nop 1
	v_writelane_b32 v249, s77, 57
	v_writelane_b32 v249, s75, 58
	v_writelane_b32 v249, s96, 59
	s_nop 1
	v_writelane_b32 v249, s97, 60
	v_writelane_b32 v249, s98, 61
	s_nop 1
	v_writelane_b32 v249, s99, 62
	v_writelane_b32 v249, s81, 63
	s_mov_b32 s28, 0
	s_branch .Lgs5_entry

.Lgs5_entry:
	s_waitcnt vmcnt(0)
	s_barrier
	s_and_saveexec_b64 s[0:1], s[76:77]
	s_cbranch_execz .LBB0_55
	v_readlane_b32 s4, v249, 37
	s_waitcnt vmcnt(0) expcnt(0) lgkmcnt(0)
	s_nop 0
	v_mov_b32_e32 v0, s4
	ds_read_b32 v2, v0
	v_readlane_b32 s4, v249, 38
	s_waitcnt lgkmcnt(0)
	v_cmp_ne_u32_e32 vcc, 0, v2
	v_mov_b32_e32 v0, s4
	ds_read_b32 v0, v0
	s_cbranch_vccnz .LBB0_711
	s_mov_b32 s10, 1
	s_branch .LBB0_699
